# DSA attend P.V loop: the 8 per-group probability reads (LDS) of a batch issued up front with counted lgkmcnt instead of read+wait per group
# speedup vs baseline: 1.0046x; 1.0046x over previous
.LBB0_275:
	v_min_i32_e32 v240, s50, v103
	v_lshl_add_u32 v240, v240, 5, v202
	ds_read_b128 v[208:211], v240
	v_add_u32_e32 v241, 4, v103
	v_min_i32_e32 v241, s50, v241
	v_lshl_add_u32 v241, v241, 5, v202
	ds_read_b128 v[212:215], v241
	v_add_u32_e32 v242, 8, v103
	v_min_i32_e32 v242, s50, v242
	v_lshl_add_u32 v242, v242, 5, v202
	ds_read_b128 v[216:219], v242
	v_add_u32_e32 v243, 12, v103
	v_min_i32_e32 v243, s50, v243
	v_lshl_add_u32 v243, v243, 5, v202
	ds_read_b128 v[220:223], v243
	v_add_u32_e32 v244, 16, v103
	v_min_i32_e32 v244, s50, v244
	v_lshl_add_u32 v244, v244, 5, v202
	ds_read_b128 v[224:227], v244
	v_add_u32_e32 v245, 20, v103
	v_min_i32_e32 v245, s50, v245
	v_lshl_add_u32 v245, v245, 5, v202
	ds_read_b128 v[228:231], v245
	v_add_u32_e32 v246, 24, v103
	v_min_i32_e32 v246, s50, v246
	v_lshl_add_u32 v246, v246, 5, v202
	ds_read_b128 v[232:235], v246
	v_add_u32_e32 v247, 28, v103
	v_min_i32_e32 v247, s50, v247
	v_lshl_add_u32 v247, v247, 5, v202
	ds_read_b128 v[236:239], v247
	v_min_i32_e32 v105, s50, v103
	v_lshl_add_u32 v105, v105, 5, v202
	v_cmp_lt_u32_e32 vcc, s50, v103
	v_lshlrev_b32_e32 v114, 16, v62
	v_and_b32_e32 v115, 0xffff0000, v62
	v_lshlrev_b32_e32 v62, 16, v63
	s_waitcnt lgkmcnt(7)
	v_cndmask_b32_e64 v110, v211, 0, vcc
	v_cndmask_b32_e64 v108, v210, 0, vcc
	v_cndmask_b32_e64 v112, v209, 0, vcc
	v_cndmask_b32_e64 v106, v208, 0, vcc
	v_and_b32_e32 v63, 0xffff0000, v63
	v_pk_fma_f32 v[88:89], v[106:107], v[62:63], v[88:89] op_sel_hi:[0,1,1]
	v_pk_fma_f32 v[86:87], v[112:113], v[62:63], v[86:87] op_sel_hi:[0,1,1]
	v_pk_fma_f32 v[84:85], v[108:109], v[62:63], v[84:85] op_sel_hi:[0,1,1]
	v_pk_fma_f32 v[82:83], v[110:111], v[62:63], v[82:83] op_sel_hi:[0,1,1]
	v_add_u32_e32 v62, 4, v103
	v_cmp_lt_u32_e32 vcc, s50, v62
	v_min_i32_e32 v62, s50, v62
	v_lshlrev_b32_e32 v116, 16, v64
	v_and_b32_e32 v117, 0xffff0000, v64
	v_lshlrev_b32_e32 v64, 16, v65
	v_and_b32_e32 v65, 0xffff0000, v65
	v_lshl_add_u32 v62, v62, 5, v202
	v_pk_fma_f32 v[72:73], v[106:107], v[64:65], v[72:73] op_sel_hi:[0,1,1]
	v_pk_fma_f32 v[70:71], v[112:113], v[64:65], v[70:71] op_sel_hi:[0,1,1]
	v_pk_fma_f32 v[68:69], v[108:109], v[64:65], v[68:69] op_sel_hi:[0,1,1]
	v_pk_fma_f32 v[66:67], v[110:111], v[64:65], v[66:67] op_sel_hi:[0,1,1]
	v_pk_fma_f32 v[92:93], v[106:107], v[114:115], v[92:93] op_sel_hi:[0,1,1]
	v_pk_fma_f32 v[80:81], v[106:107], v[116:117], v[80:81] op_sel_hi:[0,1,1]
	v_pk_fma_f32 v[94:95], v[108:109], v[114:115], v[94:95] op_sel_hi:[0,1,1]
	v_pk_fma_f32 v[74:75], v[108:109], v[116:117], v[74:75] op_sel_hi:[0,1,1]
	v_pk_fma_f32 v[90:91], v[110:111], v[114:115], v[90:91] op_sel_hi:[0,1,1]
	v_pk_fma_f32 v[76:77], v[110:111], v[116:117], v[76:77] op_sel_hi:[0,1,1]
	s_waitcnt lgkmcnt(6)
	v_cndmask_b32_e64 v106, v215, 0, vcc
	v_cndmask_b32_e64 v64, v214, 0, vcc
	v_cndmask_b32_e64 v108, v213, 0, vcc
	v_cndmask_b32_e64 v62, v212, 0, vcc
	v_lshlrev_b32_e32 v110, 16, v58
	v_and_b32_e32 v111, 0xffff0000, v58
	v_lshlrev_b32_e32 v58, 16, v59
	v_and_b32_e32 v59, 0xffff0000, v59
	v_pk_fma_f32 v[88:89], v[62:63], v[58:59], v[88:89] op_sel_hi:[0,1,1]
	v_pk_fma_f32 v[86:87], v[108:109], v[58:59], v[86:87] op_sel_hi:[0,1,1]
	v_pk_fma_f32 v[84:85], v[64:65], v[58:59], v[84:85] op_sel_hi:[0,1,1]
	v_pk_fma_f32 v[82:83], v[106:107], v[58:59], v[82:83] op_sel_hi:[0,1,1]
	v_add_u32_e32 v58, 8, v103
	v_cmp_lt_u32_e32 vcc, s50, v58
	v_min_i32_e32 v58, s50, v58
	v_pk_fma_f32 v[96:97], v[112:113], v[114:115], v[96:97] op_sel_hi:[0,1,1]
	v_pk_fma_f32 v[78:79], v[112:113], v[116:117], v[78:79] op_sel_hi:[0,1,1]
	v_lshlrev_b32_e32 v112, 16, v60
	v_and_b32_e32 v113, 0xffff0000, v60
	v_lshlrev_b32_e32 v60, 16, v61
	v_and_b32_e32 v61, 0xffff0000, v61
	v_lshl_add_u32 v58, v58, 5, v202
	v_pk_fma_f32 v[72:73], v[62:63], v[60:61], v[72:73] op_sel_hi:[0,1,1]
	v_pk_fma_f32 v[70:71], v[108:109], v[60:61], v[70:71] op_sel_hi:[0,1,1]
	v_pk_fma_f32 v[68:69], v[64:65], v[60:61], v[68:69] op_sel_hi:[0,1,1]
	v_pk_fma_f32 v[66:67], v[106:107], v[60:61], v[66:67] op_sel_hi:[0,1,1]
	v_pk_fma_f32 v[80:81], v[62:63], v[112:113], v[80:81] op_sel_hi:[0,1,1]
	v_pk_fma_f32 v[62:63], v[62:63], v[110:111], v[92:93] op_sel_hi:[0,1,1]
	v_pk_fma_f32 v[92:93], v[108:109], v[110:111], v[96:97] op_sel_hi:[0,1,1]
	v_pk_fma_f32 v[74:75], v[64:65], v[112:113], v[74:75] op_sel_hi:[0,1,1]
	v_pk_fma_f32 v[64:65], v[64:65], v[110:111], v[94:95] op_sel_hi:[0,1,1]
	v_pk_fma_f32 v[76:77], v[106:107], v[112:113], v[76:77] op_sel_hi:[0,1,1]
	v_pk_fma_f32 v[90:91], v[106:107], v[110:111], v[90:91] op_sel_hi:[0,1,1]
	s_waitcnt lgkmcnt(5)
	v_cndmask_b32_e64 v94, v219, 0, vcc
	v_cndmask_b32_e64 v60, v218, 0, vcc
	v_cndmask_b32_e64 v96, v217, 0, vcc
	v_cndmask_b32_e64 v58, v216, 0, vcc
	v_lshlrev_b32_e32 v106, 16, v54
	v_and_b32_e32 v107, 0xffff0000, v54
	v_lshlrev_b32_e32 v54, 16, v55
	v_and_b32_e32 v55, 0xffff0000, v55
	v_pk_fma_f32 v[88:89], v[58:59], v[54:55], v[88:89] op_sel_hi:[0,1,1]
	v_pk_fma_f32 v[86:87], v[96:97], v[54:55], v[86:87] op_sel_hi:[0,1,1]
	v_pk_fma_f32 v[84:85], v[60:61], v[54:55], v[84:85] op_sel_hi:[0,1,1]
	v_pk_fma_f32 v[82:83], v[94:95], v[54:55], v[82:83] op_sel_hi:[0,1,1]
	v_add_u32_e32 v54, 12, v103
	v_cmp_lt_u32_e32 vcc, s50, v54
	v_min_i32_e32 v54, s50, v54
	v_pk_fma_f32 v[78:79], v[108:109], v[112:113], v[78:79] op_sel_hi:[0,1,1]
	v_lshlrev_b32_e32 v108, 16, v56
	v_and_b32_e32 v109, 0xffff0000, v56
	v_lshlrev_b32_e32 v56, 16, v57
	v_and_b32_e32 v57, 0xffff0000, v57
	v_lshl_add_u32 v54, v54, 5, v202
	v_pk_fma_f32 v[62:63], v[58:59], v[106:107], v[62:63] op_sel_hi:[0,1,1]
	v_pk_fma_f32 v[80:81], v[58:59], v[108:109], v[80:81] op_sel_hi:[0,1,1]
	v_pk_fma_f32 v[58:59], v[58:59], v[56:57], v[72:73] op_sel_hi:[0,1,1]
	v_pk_fma_f32 v[70:71], v[96:97], v[56:57], v[70:71] op_sel_hi:[0,1,1]
	v_pk_fma_f32 v[64:65], v[60:61], v[106:107], v[64:65] op_sel_hi:[0,1,1]
	v_pk_fma_f32 v[74:75], v[60:61], v[108:109], v[74:75] op_sel_hi:[0,1,1]
	v_pk_fma_f32 v[60:61], v[60:61], v[56:57], v[68:69] op_sel_hi:[0,1,1]
	v_pk_fma_f32 v[66:67], v[94:95], v[56:57], v[66:67] op_sel_hi:[0,1,1]
	v_pk_fma_f32 v[72:73], v[96:97], v[106:107], v[92:93] op_sel_hi:[0,1,1]
	v_pk_fma_f32 v[78:79], v[96:97], v[108:109], v[78:79] op_sel_hi:[0,1,1]
	v_pk_fma_f32 v[68:69], v[94:95], v[106:107], v[90:91] op_sel_hi:[0,1,1]
	v_pk_fma_f32 v[76:77], v[94:95], v[108:109], v[76:77] op_sel_hi:[0,1,1]
	s_waitcnt lgkmcnt(4)
	v_cndmask_b32_e64 v90, v223, 0, vcc
	v_cndmask_b32_e64 v56, v222, 0, vcc
	v_cndmask_b32_e64 v92, v221, 0, vcc
	v_cndmask_b32_e64 v54, v220, 0, vcc
	v_lshlrev_b32_e32 v94, 16, v50
	v_and_b32_e32 v95, 0xffff0000, v50
	v_lshlrev_b32_e32 v50, 16, v51
	v_and_b32_e32 v51, 0xffff0000, v51
	v_lshlrev_b32_e32 v96, 16, v52
	v_and_b32_e32 v97, 0xffff0000, v52
	v_lshlrev_b32_e32 v52, 16, v53
	v_and_b32_e32 v53, 0xffff0000, v53
	v_pk_fma_f32 v[58:59], v[54:55], v[52:53], v[58:59] op_sel_hi:[0,1,1]
	v_pk_fma_f32 v[80:81], v[54:55], v[96:97], v[80:81] op_sel_hi:[0,1,1]
	v_pk_fma_f32 v[88:89], v[54:55], v[50:51], v[88:89] op_sel_hi:[0,1,1]
	v_pk_fma_f32 v[54:55], v[54:55], v[94:95], v[62:63] op_sel_hi:[0,1,1]
	v_pk_fma_f32 v[62:63], v[92:93], v[52:53], v[70:71] op_sel_hi:[0,1,1]
	v_pk_fma_f32 v[70:71], v[92:93], v[96:97], v[78:79] op_sel_hi:[0,1,1]
	v_pk_fma_f32 v[78:79], v[92:93], v[50:51], v[86:87] op_sel_hi:[0,1,1]
	v_pk_fma_f32 v[60:61], v[56:57], v[52:53], v[60:61] op_sel_hi:[0,1,1]
	v_pk_fma_f32 v[74:75], v[56:57], v[96:97], v[74:75] op_sel_hi:[0,1,1]
	v_pk_fma_f32 v[84:85], v[56:57], v[50:51], v[84:85] op_sel_hi:[0,1,1]
	v_pk_fma_f32 v[56:57], v[56:57], v[94:95], v[64:65] op_sel_hi:[0,1,1]
	v_pk_fma_f32 v[64:65], v[90:91], v[52:53], v[66:67] op_sel_hi:[0,1,1]
	v_pk_fma_f32 v[66:67], v[90:91], v[96:97], v[76:77] op_sel_hi:[0,1,1]
	v_pk_fma_f32 v[76:77], v[90:91], v[50:51], v[82:83] op_sel_hi:[0,1,1]
	v_add_u32_e32 v50, 16, v103
	v_cmp_lt_u32_e32 vcc, s50, v50
	v_min_i32_e32 v50, s50, v50
	v_lshl_add_u32 v50, v50, 5, v202
	v_pk_fma_f32 v[72:73], v[92:93], v[94:95], v[72:73] op_sel_hi:[0,1,1]
	v_pk_fma_f32 v[68:69], v[90:91], v[94:95], v[68:69] op_sel_hi:[0,1,1]
	v_lshlrev_b32_e32 v90, 16, v46
	v_and_b32_e32 v91, 0xffff0000, v46
	s_waitcnt lgkmcnt(3)
	v_cndmask_b32_e64 v82, v227, 0, vcc
	v_cndmask_b32_e64 v52, v226, 0, vcc
	v_cndmask_b32_e64 v86, v225, 0, vcc
	v_cndmask_b32_e64 v50, v224, 0, vcc
	v_lshlrev_b32_e32 v46, 16, v47
	v_and_b32_e32 v47, 0xffff0000, v47
	v_lshlrev_b32_e32 v92, 16, v48
	v_and_b32_e32 v93, 0xffff0000, v48
	v_lshlrev_b32_e32 v48, 16, v49
	v_and_b32_e32 v49, 0xffff0000, v49
	v_pk_fma_f32 v[54:55], v[50:51], v[90:91], v[54:55] op_sel_hi:[0,1,1]
	v_pk_fma_f32 v[88:89], v[50:51], v[46:47], v[88:89] op_sel_hi:[0,1,1]
	v_pk_fma_f32 v[80:81], v[50:51], v[92:93], v[80:81] op_sel_hi:[0,1,1]
	v_pk_fma_f32 v[50:51], v[50:51], v[48:49], v[58:59] op_sel_hi:[0,1,1]
	v_pk_fma_f32 v[58:59], v[86:87], v[90:91], v[72:73] op_sel_hi:[0,1,1]
	v_pk_fma_f32 v[72:73], v[86:87], v[46:47], v[78:79] op_sel_hi:[0,1,1]
	v_pk_fma_f32 v[56:57], v[52:53], v[90:91], v[56:57] op_sel_hi:[0,1,1]
	v_pk_fma_f32 v[78:79], v[52:53], v[46:47], v[84:85] op_sel_hi:[0,1,1]
	v_pk_fma_f32 v[74:75], v[52:53], v[92:93], v[74:75] op_sel_hi:[0,1,1]
	v_pk_fma_f32 v[52:53], v[52:53], v[48:49], v[60:61] op_sel_hi:[0,1,1]
	v_pk_fma_f32 v[60:61], v[82:83], v[90:91], v[68:69] op_sel_hi:[0,1,1]
	v_pk_fma_f32 v[68:69], v[82:83], v[46:47], v[76:77] op_sel_hi:[0,1,1]
	v_add_u32_e32 v46, 20, v103
	v_cmp_lt_u32_e32 vcc, s50, v46
	v_min_i32_e32 v46, s50, v46
	v_lshl_add_u32 v46, v46, 5, v202
	v_pk_fma_f32 v[62:63], v[86:87], v[48:49], v[62:63] op_sel_hi:[0,1,1]
	v_pk_fma_f32 v[64:65], v[82:83], v[48:49], v[64:65] op_sel_hi:[0,1,1]
	v_pk_fma_f32 v[70:71], v[86:87], v[92:93], v[70:71] op_sel_hi:[0,1,1]
	v_pk_fma_f32 v[66:67], v[82:83], v[92:93], v[66:67] op_sel_hi:[0,1,1]
	v_lshlrev_b32_e32 v84, 16, v10
	v_and_b32_e32 v85, 0xffff0000, v10
	s_waitcnt lgkmcnt(2)
	v_cndmask_b32_e64 v76, v231, 0, vcc
	v_cndmask_b32_e64 v48, v230, 0, vcc
	v_cndmask_b32_e64 v82, v229, 0, vcc
	v_cndmask_b32_e64 v46, v228, 0, vcc
	v_lshlrev_b32_e32 v10, 16, v11
	v_and_b32_e32 v11, 0xffff0000, v11
	v_lshlrev_b32_e32 v86, 16, v12
	v_and_b32_e32 v87, 0xffff0000, v12
	v_lshlrev_b32_e32 v12, 16, v13
	v_and_b32_e32 v13, 0xffff0000, v13
	v_pk_fma_f32 v[50:51], v[46:47], v[12:13], v[50:51] op_sel_hi:[0,1,1]
	v_pk_fma_f32 v[80:81], v[46:47], v[86:87], v[80:81] op_sel_hi:[0,1,1]
	v_pk_fma_f32 v[88:89], v[46:47], v[10:11], v[88:89] op_sel_hi:[0,1,1]
	v_pk_fma_f32 v[46:47], v[46:47], v[84:85], v[54:55] op_sel_hi:[0,1,1]
	v_pk_fma_f32 v[54:55], v[82:83], v[12:13], v[62:63] op_sel_hi:[0,1,1]
	v_pk_fma_f32 v[62:63], v[82:83], v[86:87], v[70:71] op_sel_hi:[0,1,1]
	v_pk_fma_f32 v[70:71], v[82:83], v[10:11], v[72:73] op_sel_hi:[0,1,1]
	v_pk_fma_f32 v[52:53], v[48:49], v[12:13], v[52:53] op_sel_hi:[0,1,1]
	v_pk_fma_f32 v[72:73], v[48:49], v[86:87], v[74:75] op_sel_hi:[0,1,1]
	v_pk_fma_f32 v[74:75], v[48:49], v[10:11], v[78:79] op_sel_hi:[0,1,1]
	v_pk_fma_f32 v[48:49], v[48:49], v[84:85], v[56:57] op_sel_hi:[0,1,1]
	v_pk_fma_f32 v[56:57], v[76:77], v[12:13], v[64:65] op_sel_hi:[0,1,1]
	v_pk_fma_f32 v[64:65], v[76:77], v[86:87], v[66:67] op_sel_hi:[0,1,1]
	v_pk_fma_f32 v[66:67], v[76:77], v[10:11], v[68:69] op_sel_hi:[0,1,1]
	v_add_u32_e32 v10, 24, v103
	v_cmp_lt_u32_e32 vcc, s50, v10
	v_min_i32_e32 v10, s50, v10
	v_lshl_add_u32 v10, v10, 5, v202
	v_pk_fma_f32 v[58:59], v[82:83], v[84:85], v[58:59] op_sel_hi:[0,1,1]
	v_pk_fma_f32 v[60:61], v[76:77], v[84:85], v[60:61] op_sel_hi:[0,1,1]
	v_lshlrev_b32_e32 v78, 16, v6
	v_and_b32_e32 v79, 0xffff0000, v6
	s_waitcnt lgkmcnt(1)
	v_cndmask_b32_e64 v68, v235, 0, vcc
	v_cndmask_b32_e64 v12, v234, 0, vcc
	v_cndmask_b32_e64 v76, v233, 0, vcc
	v_cndmask_b32_e64 v10, v232, 0, vcc
	v_lshlrev_b32_e32 v6, 16, v7
	v_and_b32_e32 v7, 0xffff0000, v7
	v_lshlrev_b32_e32 v82, 16, v8
	v_and_b32_e32 v83, 0xffff0000, v8
	v_lshlrev_b32_e32 v8, 16, v9
	v_and_b32_e32 v9, 0xffff0000, v9
	v_pk_fma_f32 v[46:47], v[10:11], v[78:79], v[46:47] op_sel_hi:[0,1,1]
	v_pk_fma_f32 v[84:85], v[10:11], v[6:7], v[88:89] op_sel_hi:[0,1,1]
	v_pk_fma_f32 v[80:81], v[10:11], v[82:83], v[80:81] op_sel_hi:[0,1,1]
	v_pk_fma_f32 v[10:11], v[10:11], v[8:9], v[50:51] op_sel_hi:[0,1,1]
	v_pk_fma_f32 v[50:51], v[76:77], v[78:79], v[58:59] op_sel_hi:[0,1,1]
	v_pk_fma_f32 v[58:59], v[76:77], v[6:7], v[70:71] op_sel_hi:[0,1,1]
	v_pk_fma_f32 v[62:63], v[76:77], v[82:83], v[62:63] op_sel_hi:[0,1,1]
	v_pk_fma_f32 v[54:55], v[76:77], v[8:9], v[54:55] op_sel_hi:[0,1,1]
	v_pk_fma_f32 v[48:49], v[12:13], v[78:79], v[48:49] op_sel_hi:[0,1,1]
	v_pk_fma_f32 v[76:77], v[12:13], v[6:7], v[74:75] op_sel_hi:[0,1,1]
	v_pk_fma_f32 v[74:75], v[12:13], v[82:83], v[72:73] op_sel_hi:[0,1,1]
	v_pk_fma_f32 v[12:13], v[12:13], v[8:9], v[52:53] op_sel_hi:[0,1,1]
	v_pk_fma_f32 v[52:53], v[68:69], v[78:79], v[60:61] op_sel_hi:[0,1,1]
	v_pk_fma_f32 v[60:61], v[68:69], v[6:7], v[66:67] op_sel_hi:[0,1,1]
	v_add_u32_e32 v6, 28, v103
	v_cmp_lt_u32_e32 vcc, s50, v6
	v_min_i32_e32 v6, s50, v6
	v_lshl_add_u32 v6, v6, 5, v202
	v_pk_fma_f32 v[56:57], v[68:69], v[8:9], v[56:57] op_sel_hi:[0,1,1]
	v_pk_fma_f32 v[64:65], v[68:69], v[82:83], v[64:65] op_sel_hi:[0,1,1]
	v_lshlrev_b32_e32 v106, 16, v2
	v_and_b32_e32 v107, 0xffff0000, v2
	v_lshlrev_b32_e32 v2, 16, v3
	s_waitcnt lgkmcnt(0)
	v_cndmask_b32_e64 v90, v239, 0, vcc
	v_cndmask_b32_e64 v8, v238, 0, vcc
	v_cndmask_b32_e64 v66, v237, 0, vcc
	v_cndmask_b32_e64 v6, v236, 0, vcc
	v_and_b32_e32 v3, 0xffff0000, v3
	v_lshlrev_b32_e32 v82, 16, v4
	v_and_b32_e32 v83, 0xffff0000, v4
	v_lshlrev_b32_e32 v4, 16, v5
	v_and_b32_e32 v5, 0xffff0000, v5
	v_pk_fma_f32 v[72:73], v[6:7], v[4:5], v[10:11] op_sel_hi:[0,1,1]
	v_pk_fma_f32 v[80:81], v[6:7], v[82:83], v[80:81] op_sel_hi:[0,1,1]
	v_pk_fma_f32 v[88:89], v[6:7], v[2:3], v[84:85] op_sel_hi:[0,1,1]
	v_pk_fma_f32 v[92:93], v[6:7], v[106:107], v[46:47] op_sel_hi:[0,1,1]
	v_pk_fma_f32 v[70:71], v[66:67], v[4:5], v[54:55] op_sel_hi:[0,1,1]
	v_pk_fma_f32 v[78:79], v[66:67], v[82:83], v[62:63] op_sel_hi:[0,1,1]
	v_pk_fma_f32 v[86:87], v[66:67], v[2:3], v[58:59] op_sel_hi:[0,1,1]
	v_pk_fma_f32 v[96:97], v[66:67], v[106:107], v[50:51] op_sel_hi:[0,1,1]
	v_pk_fma_f32 v[68:69], v[8:9], v[4:5], v[12:13] op_sel_hi:[0,1,1]
	v_pk_fma_f32 v[74:75], v[8:9], v[82:83], v[74:75] op_sel_hi:[0,1,1]
	v_pk_fma_f32 v[84:85], v[8:9], v[2:3], v[76:77] op_sel_hi:[0,1,1]
	v_pk_fma_f32 v[94:95], v[8:9], v[106:107], v[48:49] op_sel_hi:[0,1,1]
	v_pk_fma_f32 v[66:67], v[90:91], v[4:5], v[56:57] op_sel_hi:[0,1,1]
	v_pk_fma_f32 v[76:77], v[90:91], v[82:83], v[64:65] op_sel_hi:[0,1,1]
	v_pk_fma_f32 v[82:83], v[90:91], v[2:3], v[60:61] op_sel_hi:[0,1,1]
	v_pk_fma_f32 v[90:91], v[90:91], v[106:107], v[52:53] op_sel_hi:[0,1,1]
	s_add_i32 s76, s76, 8
	s_andn2_b64 vcc, exec, s[34:35]
	v_mov_b32_e32 v103, v104
	s_waitcnt vmcnt(0)
	v_mov_b64_e32 v[2:3], v[42:43]
	v_mov_b64_e32 v[4:5], v[44:45]
	v_mov_b64_e32 v[6:7], v[38:39]
	v_mov_b64_e32 v[8:9], v[40:41]
	v_mov_b64_e32 v[10:11], v[34:35]
	v_mov_b64_e32 v[12:13], v[36:37]
	v_mov_b64_e32 v[46:47], v[30:31]
	v_mov_b64_e32 v[48:49], v[32:33]
	v_mov_b64_e32 v[50:51], v[26:27]
	v_mov_b64_e32 v[52:53], v[28:29]
	v_mov_b64_e32 v[54:55], v[22:23]
	v_mov_b64_e32 v[56:57], v[24:25]
	v_mov_b64_e32 v[58:59], v[18:19]
	v_mov_b64_e32 v[60:61], v[20:21]
	v_mov_b64_e32 v[62:63], v[14:15]
	v_mov_b64_e32 v[64:65], v[16:17]
	s_cbranch_vccz .LBB0_241
